# v43_q4
# baseline (speedup 1.0000x reference)
; __global__ void __launch_bounds__(512) fwd(Args a_) {
;     ...
;         } else if (PHM(3) && sp == 3) { PHASE_PROLOGUE
;             const unsigned* kmx = (const unsigned*)(a.ws + WS_CTL) + 8192 + 64 * (8 + 2 * L);
;             const float kb0 = 8.f * 1.01f * __uint_as_float(kmx[0]), kb1 = 8.f * 1.01f * __uint_as_float(kmx[64]);
;             const int gwx = ((G & 7) == 0 ? (bx & 7) * (G >> 3) + (bx >> 3) : bx) * 8 + wave;
;             for (int k = gwx; k < 2048; k += NGW) { nsa_item8(c, 2047 - (k >> 1), 1 - (k & 1), lds, wave, lane, (k & 1) ? kb0 : kb1); nsa_item8(c, k >> 1, k & 1, lds, wave, lane, (k & 1) ? kb1 : kb0); }
.LBB0_158:
	s_and_b64 vcc, exec, s[6:7]
	s_cbranch_vccz .LBB0_1228
	s_cmp_gt_i32 s44, 1
	s_mov_b64 s[6:7], -1
	s_cbranch_scc0 .LBB0_1173
	s_cmp_gt_i32 s44, 2
	v_writelane_b32 v244, s84, 28
	s_cbranch_scc0 .LBB0_1098
	v_readlane_b32 s101, v244, 7
	v_readlane_b32 s84, v244, 28
	s_nop 1
	s_bitcmp1_b32 s101, 0
	s_cbranch_scc0 .Lcq_p3_cont
	v_writelane_b32 v246, 4, 1
	s_lshl_b32 s100, s84, 1
	s_add_i32 s100, s100, 9
	s_branch .Lcq_entry
